# speedup vs baseline: 1.0062x; 1.0062x over previous
; __device__ __forceinline__ void attn_unit(LAS unsigned char* lds, bf16_t* Qm, const bf16_t* __restrict__ Kb, const bf16_t* __restrict__ Vt,
;                                           int b, int h, int qb, int lgS, float lam, float oscale, const float* __restrict__ subg, float* stash) {
;     ...
;             ATT_QK(p0, p1);
;             __builtin_amdgcn_s_setprio(0);
;             ATT_SB();
; #pragma unroll
;             for (int b2 = 0; b2 < 4; ++b2) vfb[b2] = *(const LAS bf16x8*)(lds + vs0 + vr + b2 * 32 * VP + 32);
;             float mxa, mxb;
;             o[0] = __builtin_amdgcn_mfma_f32_32x32x16_bf16(vfa[0], __builtin_bit_cast(bf16x8, pk[0]), o[0], 0, 0, 0);
;             mxa = ATT_MX3(p0[0], p0[1], p1[0]); mxb = ATT_MX3(p0[2], p0[3], p1[1]); mxa = ATT_MX3(mxa, p1[2], p1[3]); mxa = ATT_MX3(mxa, p0[4], p0[5]); mxb = ATT_MX3(mxb, p0[6], p0[7]);
;             ATT_SB();
;             o[1] = __builtin_amdgcn_mfma_f32_32x32x16_bf16(vfa[1], __builtin_bit_cast(bf16x8, pk[0]), o[1], 0, 0, 0);
;             mxa = ATT_MX3(mxa, p1[4], p1[5]); mxb = ATT_MX3(mxb, p1[6], p1[7]); mxa = ATT_MX3(mxa, p0[8], p0[9]); mxb = ATT_MX3(mxb, p0[10], p0[11]); mxa = ATT_MX3(mxa, p1[8], p1[9]);
;             ATT_SB();
;             o[2] = __builtin_amdgcn_mfma_f32_32x32x16_bf16(vfa[2], __builtin_bit_cast(bf16x8, pk[0]), o[2], 0, 0, 0);
;             mxb = ATT_MX3(mxb, p1[10], p1[11]); mxa = ATT_MX3(mxa, p0[12], p0[13]); mxb = ATT_MX3(mxb, p0[14], p0[15]); mxa = ATT_MX3(mxa, p1[12], p1[13]); mxb = ATT_MX3(mxb, p1[14], p1[15]);
;             ATT_SB();
;             o[3] = __builtin_amdgcn_mfma_f32_32x32x16_bf16(vfa[3], __builtin_bit_cast(bf16x8, pk[0]), o[3], 0, 0, 0);
;             float mx;
;             { const float m_ = __builtin_fmaxf(mxa, mxb); auto rr_ = __builtin_amdgcn_permlane32_swap(__float_as_uint(m_), __float_as_uint(m_), false, false);
;               mx = __builtin_fmaxf(__uint_as_float(rr_[0]), __uint_as_float(rr_[1])); }
;             ATT_SB();
;             if (__builtin_expect(__any(mx > 8.0f), 0)) {
;                 const float dl = (mx > 8.0f) ? mx : 0.f;
;                 mhat += dl;
; #pragma unroll
;                 for (int r = 0; r < 16; ++r) { p0[r] -= dl; p1[r] -= dl; }
;                 const float f = __builtin_amdgcn_exp2f(-dl);
;                 lrun *= f;
; #pragma unroll
;                 for (int i = 0; i < 4; ++i) o[i] = o[i] * f;
; #pragma unroll
.LBB0_341:
	v_add_u32_e32 v80, s61, v235
	ds_read_b128 v[204:207], v80 offset:2112
	ds_read_b128 v[208:211], v80 offset:2624
	ds_read_b128 v[212:215], v80 offset:4224
	ds_read_b128 v[216:219], v80 offset:4736
	ds_read_b128 v[222:225], v80 offset:6336
	ds_read_b128 v[240:243], v80 offset:6848
	s_setprio 1
	v_mfma_f32_32x32x16_bf16 v[96:111], v[156:159], v[136:139], v[64:79]
	v_mfma_f32_32x32x16_bf16 v[80:95], v[160:163], v[136:139], v[64:79]
	s_setprio 0
	s_waitcnt lgkmcnt(5)
	v_mfma_f32_32x32x16_bf16 v[96:111], v[204:207], v[140:143], v[96:111]
	v_add_u32_e32 v251, s65, v220
	s_waitcnt lgkmcnt(4)
	v_mfma_f32_32x32x16_bf16 v[80:95], v[208:211], v[140:143], v[80:95]
	s_waitcnt lgkmcnt(3)
	v_mfma_f32_32x32x16_bf16 v[96:111], v[212:215], v[144:147], v[96:111]
	s_waitcnt lgkmcnt(2)
	v_mfma_f32_32x32x16_bf16 v[80:95], v[216:219], v[144:147], v[80:95]
	ds_read_b128 v[216:219], v251 offset:25376
	ds_read_b128 v[212:215], v251 offset:29984
	ds_read_b128 v[208:211], v251 offset:34592
	ds_read_b128 v[204:207], v251 offset:39200
	s_waitcnt lgkmcnt(5)
	v_mfma_f32_32x32x16_bf16 v[96:111], v[222:225], v[148:151], v[96:111]
	s_waitcnt lgkmcnt(4)
	v_mfma_f32_32x32x16_bf16 v[80:95], v[240:243], v[148:151], v[80:95]
	s_nop 9
	v_max_f32_e32 v222, v97, v97
	v_max_f32_e32 v223, v96, v96
	v_max_f32_e32 v222, v223, v222
	v_mfma_f32_32x32x16_bf16 v[0:15], v[196:199], v[200:203], v[0:15]
	v_max3_f32 v223, v98, v99, v81
	v_max3_f32 v222, v222, v80, v82
	v_max3_f32 v222, v222, v83, v100
	v_max3_f32 v223, v223, v102, v103
	v_mfma_f32_32x32x16_bf16 v[48:63], v[192:195], v[200:203], v[48:63]
	v_max3_f32 v192, v222, v101, v84
	v_max3_f32 v193, v223, v86, v87
	v_max3_f32 v192, v192, v85, v104
	v_max3_f32 v193, v193, v106, v107
	v_max3_f32 v192, v192, v105, v88
	v_mfma_f32_32x32x16_bf16 v[32:47], v[188:191], v[200:203], v[32:47]
	v_max3_f32 v188, v193, v90, v91
	v_max3_f32 v189, v192, v89, v108
	v_max3_f32 v188, v188, v110, v111
	v_max3_f32 v189, v189, v109, v92
	v_max3_f32 v188, v188, v94, v95
	v_mfma_f32_32x32x16_bf16 v[16:31], v[184:187], v[200:203], v[16:31]
	v_max3_f32 v184, v189, v93, v188
	v_mov_b32_e32 v185, v184
	s_nop 1
	v_permlane32_swap_b32_e32 v184, v185
	v_max_f32_e32 v185, v185, v185
	v_max_f32_e32 v184, v184, v184
	v_max_f32_e32 v184, v184, v185
	s_mov_b32 s30, 0x41000000
	v_cmp_lt_f32_e32 vcc, s30, v184
	s_cbranch_vccnz .LBB0_348
.LBB0_342:
	v_exp_f32_e32 v96, v96
	s_waitcnt lgkmcnt(3)
	v_mfma_f32_32x32x16_bf16 v[0:15], v[216:219], v[180:183], v[0:15]
	v_exp_f32_e32 v97, v97
	ds_read_b128 v[192:195], v251 offset:25408
	ds_read_b128 v[196:199], v251 offset:30016
	ds_read_b128 v[188:191], v251 offset:34624
	ds_read_b128 v[184:187], v251 offset:39232
	v_exp_f32_e32 v88, v88
	v_add_f32_e32 v200, 0, v96
	v_exp_f32_e32 v89, v89
	v_add_f32_e32 v200, v97, v200
	s_nop 0
	v_add_f32_e32 v200, v88, v200
	v_add_f32_e32 v200, v89, v200
	v_exp_f32_e32 v98, v98
	s_waitcnt lgkmcnt(6)
	v_mfma_f32_32x32x16_bf16 v[48:63], v[212:215], v[180:183], v[48:63]
	v_exp_f32_e32 v99, v99
	v_exp_f32_e32 v90, v90
	v_add_f32_e32 v200, v98, v200
	v_exp_f32_e32 v91, v91
	v_add_f32_e32 v200, v99, v200
	s_nop 0
	v_add_f32_e32 v200, v90, v200
	v_add_f32_e32 v200, v91, v200
	v_exp_f32_e32 v100, v100
	s_waitcnt lgkmcnt(5)
	v_mfma_f32_32x32x16_bf16 v[32:47], v[208:211], v[180:183], v[32:47]
	v_exp_f32_e32 v101, v101
	v_exp_f32_e32 v92, v92
	v_add_f32_e32 v200, v100, v200
	v_exp_f32_e32 v93, v93
	v_add_f32_e32 v200, v101, v200
	s_nop 0
	v_add_f32_e32 v200, v92, v200
	v_add_f32_e32 v200, v93, v200
	v_exp_f32_e32 v102, v102
	s_waitcnt lgkmcnt(4)
	v_mfma_f32_32x32x16_bf16 v[16:31], v[204:207], v[180:183], v[16:31]
	v_exp_f32_e32 v103, v103
	v_exp_f32_e32 v94, v94
	v_add_f32_e32 v180, v102, v200
	v_exp_f32_e32 v95, v95
	v_add_f32_e32 v180, v103, v180
	s_nop 0
	v_add_f32_e32 v180, v94, v180
	v_add_f32_e32 v212, v95, v180
	s_waitcnt lgkmcnt(3)
	v_mfma_f32_32x32x16_bf16 v[0:15], v[192:195], v[172:175], v[0:15]
	ds_read_b128 v[180:183], v251 offset:25440
	ds_read_b128 v[200:203], v251 offset:30048
	ds_read_b128 v[204:207], v251 offset:34656
	ds_read_b128 v[208:211], v251 offset:39264
	v_exp_f32_e32 v104, v104
	v_exp_f32_e32 v105, v105
	v_add_f32_e32 v216, v104, v212
	v_add_f32_e32 v216, v105, v216
	v_add_u32_e32 v251, s25, v220
	s_waitcnt lgkmcnt(6)
	v_mfma_f32_32x32x16_bf16 v[48:63], v[196:199], v[172:175], v[48:63]
	ds_read_b128 v[192:195], v251 offset:29952
	v_exp_f32_e32 v106, v106
	v_exp_f32_e32 v107, v107
	v_add_f32_e32 v216, v106, v216
	v_add_f32_e32 v216, v107, v216
	s_waitcnt lgkmcnt(6)
	v_mfma_f32_32x32x16_bf16 v[32:47], v[188:191], v[172:175], v[32:47]
	ds_read_b128 v[196:199], v251 offset:25344
	v_exp_f32_e32 v108, v108
	v_exp_f32_e32 v109, v109
	v_add_f32_e32 v216, v108, v216
	v_add_f32_e32 v216, v109, v216
	s_waitcnt lgkmcnt(6)
	v_mfma_f32_32x32x16_bf16 v[16:31], v[184:187], v[172:175], v[16:31]
	ds_read_b128 v[188:191], v251 offset:34560
	v_exp_f32_e32 v110, v110
	v_exp_f32_e32 v111, v111
	v_add_f32_e32 v216, v110, v216
	v_add_f32_e32 v216, v111, v216
	s_waitcnt lgkmcnt(6)
	v_mfma_f32_32x32x16_bf16 v[0:15], v[180:183], v[164:167], v[0:15]
	ds_read_b128 v[184:187], v251 offset:39168
	v_exp_f32_e32 v80, v80
	v_exp_f32_e32 v81, v81
	v_add_f32_e32 v216, v80, v216
	v_add_f32_e32 v216, v81, v216
	v_cvt_pk_bf16_f32 v180, v104, v105
	v_cvt_pk_bf16_f32 v181, v106, v107
	v_cvt_pk_bf16_f32 v182, v108, v109
	v_cvt_pk_bf16_f32 v183, v110, v111
	s_waitcnt lgkmcnt(6)
	v_mfma_f32_32x32x16_bf16 v[48:63], v[200:203], v[164:167], v[48:63]
	v_exp_f32_e32 v82, v82
	v_exp_f32_e32 v83, v83
	v_add_f32_e32 v216, v82, v216
	v_add_f32_e32 v216, v83, v216
	v_cvt_pk_bf16_f32 v200, v96, v97
	v_cvt_pk_bf16_f32 v201, v98, v99
	v_cvt_pk_bf16_f32 v202, v100, v101
	v_cvt_pk_bf16_f32 v203, v102, v103
	v_cvt_pk_bf16_f32 v172, v80, v81
	s_waitcnt lgkmcnt(5)
	v_mfma_f32_32x32x16_bf16 v[32:47], v[204:207], v[164:167], v[32:47]
	v_exp_f32_e32 v84, v84
	v_exp_f32_e32 v85, v85
	v_add_f32_e32 v216, v84, v216
	v_add_f32_e32 v216, v85, v216
	v_cvt_pk_bf16_f32 v173, v82, v83
	s_waitcnt lgkmcnt(4)
	v_mfma_f32_32x32x16_bf16 v[16:31], v[208:211], v[164:167], v[16:31]
	v_exp_f32_e32 v86, v86
	v_exp_f32_e32 v87, v87
	v_add_f32_e32 v216, v86, v216
	v_add_f32_e32 v216, v87, v216
	s_andn2_b64 vcc, exec, s[28:29]
	s_cbranch_vccnz .LBB0_344
	v_add_u32_e32 v160, s50, v235
	ds_read_b128 v[156:159], v160
	ds_read_b128 v[160:163], v160 offset:512
.LBB0_344:
	v_add_f32_e32 v249, v249, v216
	v_cvt_pk_bf16_f32 v174, v84, v85
	v_cvt_pk_bf16_f32 v175, v86, v87
	v_cvt_pk_bf16_f32 v164, v88, v89
	v_cvt_pk_bf16_f32 v165, v90, v91
	v_cvt_pk_bf16_f32 v166, v92, v93
	v_cvt_pk_bf16_f32 v167, v94, v95
	s_add_i32 s57, s57, 1
	s_add_i32 s90, s90, 64
	s_mov_b64 s[28:29], 0x10000
	s_cmp_eq_u32 s63, s57
	v_lshl_add_u64 v[238:239], v[238:239], 0, s[28:29]
	s_waitcnt lgkmcnt(0)
	s_barrier
	s_cbranch_scc1 .LBB0_349
	s_mov_b32 s28, s25
	s_mov_b32 s25, s56
	s_mov_b32 s29, s60
	s_mov_b32 s60, s61
	s_mov_b32 s56, s65
	s_branch .LBB0_335
